# thin-tile LayerNorm and P0 pre-pass row all-reduce butterflies also converted to DPP + permlane swaps, on top of v064
# baseline (speedup 1.0000x reference)
; __device__ __forceinline__ unsigned pk2(float lo, float hi) { const f32x2_pk v = {lo, hi}; return __builtin_bit_cast(unsigned, __builtin_convertvector(v, bf16x2_pk)); }
; #define RS ((float*)(WSP() + WS_RS))
; template <bool HAS_G, bool HAS_PRE, bool HAS_F, bool HAS_P, bool HIN32, bool HOUT32> ...
;     ...
;         if (!HAS_G && hout_) {
; #pragma unroll
;             for (int j = 0; j < 4; ++j) { v2u w; w.x = pk2(v[j][0], v[j][1]); w.y = pk2(v[j][2], v[j][3]); *(v2u*)((bf16*)hout_ + mm * DM + 4 * lane + 256 * j) = w; } }
;         if (HAS_PRE) {
;             float ss = 0.f;
; #pragma unroll
;             for (int j = 0; j < 4; ++j) ss += (v[j][0] * v[j][0] + v[j][1] * v[j][1]) + (v[j][2] * v[j][2] + v[j][3] * v[j][3]);
;             const float r = __builtin_amdgcn_rsqf(wave_sum(ss) * (1.f / DM) + EPS)    ;
;             if (lane == 0) RS[mm] = r;
.LBB0_35:
	v_mul_f32_e32 v151, v125, v125
	v_mul_f32_e32 v153, v127, v127
	v_fmac_f32_e32 v151, v124, v124
	v_fmac_f32_e32 v153, v126, v126
	v_add_f32_e32 v151, v151, v153
	v_mul_f32_e32 v153, v121, v121
	v_mul_f32_e32 v155, v123, v123
	v_fmac_f32_e32 v153, v120, v120
	v_fmac_f32_e32 v155, v122, v122
	v_add_f32_e32 v153, v153, v155
	v_add_f32_e32 v151, v153, v151
	v_mul_f32_e32 v153, v117, v117
	v_mul_f32_e32 v155, v119, v119
	v_fmac_f32_e32 v153, v116, v116
	v_fmac_f32_e32 v155, v118, v118
	v_add_f32_e32 v153, v153, v155
	v_add_f32_e32 v151, v153, v151
	v_mul_f32_e32 v153, v113, v113
	v_mul_f32_e32 v155, v115, v115
	v_fmac_f32_e32 v153, v112, v112
	v_fmac_f32_e32 v155, v114, v114
	v_add_f32_e32 v153, v153, v155
	v_add_f32_e32 v151, v153, v151
	v_cvt_pk_bf16_f32 v172, v124, v125
	v_cvt_pk_bf16_f32 v173, v126, v127
	global_store_dwordx2 v[166:167], v[172:173], off
	v_cvt_pk_bf16_f32 v172, v120, v121
	v_cvt_pk_bf16_f32 v173, v122, v123
	global_store_dwordx2 v[166:167], v[172:173], off offset:512
	v_cvt_pk_bf16_f32 v172, v116, v117
	v_cvt_pk_bf16_f32 v173, v118, v119
	global_store_dwordx2 v[166:167], v[172:173], off offset:1024
	v_cvt_pk_bf16_f32 v172, v112, v113
	v_cvt_pk_bf16_f32 v173, v114, v115
	global_store_dwordx2 v[166:167], v[172:173], off offset:1536
	s_waitcnt lgkmcnt(0)
	s_nop 1
	v_add_f32_dpp v151, v151, v151 quad_perm:[1,0,3,2] row_mask:0xf bank_mask:0xf
	s_nop 1
	v_add_f32_dpp v151, v151, v151 quad_perm:[2,3,0,1] row_mask:0xf bank_mask:0xf
	s_nop 1
	v_add_f32_dpp v151, v151, v151 row_half_mirror row_mask:0xf bank_mask:0xf
	s_nop 1
	v_add_f32_dpp v151, v151, v151 row_mirror row_mask:0xf bank_mask:0xf
	v_mov_b32_e32 v153, v151
	s_nop 1
	v_permlane16_swap_b32_e32 v151, v153
	v_add_f32_e32 v151, v151, v153
	v_mov_b32_e32 v153, v151
	s_nop 1
	v_permlane32_swap_b32_e32 v151, v153
	v_add_f32_e32 v151, v151, v153
	v_fmamk_f32 v151, v151, 0x3a800000, v198
	v_rsq_f32_e32 v151, v151
	s_and_saveexec_b64 s[56:57], s[4:5]
	s_cbranch_execz .LBB0_37
	global_store_dword v133, v151, s[12:13]

; __device__ __forceinline__ unsigned pk2(float lo, float hi) { const f32x2_pk v = {lo, hi}; return __builtin_bit_cast(unsigned, __builtin_convertvector(v, bf16x2_pk)); }
; #define RS ((float*)(WSP() + WS_RS))
; template <bool HAS_G, bool HAS_PRE, bool HAS_F, bool HAS_P, bool HIN32, bool HOUT32> ...
;     ...
;         if (!HAS_G && hout_) {
; #pragma unroll
;             for (int j = 0; j < 4; ++j) { v2u w; w.x = pk2(v[j][0], v[j][1]); w.y = pk2(v[j][2], v[j][3]); *(v2u*)((bf16*)hout_ + mm * DM + 4 * lane + 256 * j) = w; } }
;         if (HAS_PRE) {
;             float ss = 0.f;
; #pragma unroll
;             for (int j = 0; j < 4; ++j) ss += (v[j][0] * v[j][0] + v[j][1] * v[j][1]) + (v[j][2] * v[j][2] + v[j][3] * v[j][3]);
;             const float r = __builtin_amdgcn_rsqf(wave_sum(ss) * (1.f / DM) + EPS)    ;
;             if (lane == 0) RS[mm] = r;
.LBB0_41:
	v_mul_f32_e32 v151, v109, v109
	v_mul_f32_e32 v153, v111, v111
	v_fmac_f32_e32 v151, v108, v108
	v_fmac_f32_e32 v153, v110, v110
	v_add_f32_e32 v151, v151, v153
	v_mul_f32_e32 v153, v105, v105
	v_mul_f32_e32 v155, v107, v107
	v_fmac_f32_e32 v153, v104, v104
	v_fmac_f32_e32 v155, v106, v106
	v_add_f32_e32 v153, v153, v155
	v_add_f32_e32 v151, v153, v151
	v_mul_f32_e32 v153, v101, v101
	v_mul_f32_e32 v155, v103, v103
	v_fmac_f32_e32 v153, v100, v100
	v_fmac_f32_e32 v155, v102, v102
	v_add_f32_e32 v153, v153, v155
	v_add_f32_e32 v151, v153, v151
	v_mul_f32_e32 v153, v97, v97
	v_mul_f32_e32 v155, v99, v99
	v_fmac_f32_e32 v153, v96, v96
	v_fmac_f32_e32 v155, v98, v98
	v_add_f32_e32 v153, v153, v155
	v_add_f32_e32 v151, v153, v151
	s_add_i32 s56, s76, s60
	s_ashr_i32 s57, s56, 31
	s_lshl_b64 s[58:59], s[56:57], 11
	v_lshl_add_u64 v[172:173], v[130:131], 0, s[58:59]
	v_cvt_pk_bf16_f32 v174, v108, v109
	v_cvt_pk_bf16_f32 v175, v110, v111
	global_store_dwordx2 v[172:173], v[174:175], off
	v_cvt_pk_bf16_f32 v174, v104, v105
	v_cvt_pk_bf16_f32 v175, v106, v107
	global_store_dwordx2 v[172:173], v[174:175], off offset:512
	v_cvt_pk_bf16_f32 v174, v100, v101
	v_cvt_pk_bf16_f32 v175, v102, v103
	global_store_dwordx2 v[172:173], v[174:175], off offset:1024
	v_cvt_pk_bf16_f32 v174, v96, v97
	v_cvt_pk_bf16_f32 v175, v98, v99
	global_store_dwordx2 v[172:173], v[174:175], off offset:1536
	s_waitcnt lgkmcnt(0)
	s_nop 1
	v_add_f32_dpp v151, v151, v151 quad_perm:[1,0,3,2] row_mask:0xf bank_mask:0xf
	s_nop 1
	v_add_f32_dpp v151, v151, v151 quad_perm:[2,3,0,1] row_mask:0xf bank_mask:0xf
	s_nop 1
	v_add_f32_dpp v151, v151, v151 row_half_mirror row_mask:0xf bank_mask:0xf
	s_nop 1
	v_add_f32_dpp v151, v151, v151 row_mirror row_mask:0xf bank_mask:0xf
	v_mov_b32_e32 v153, v151
	s_nop 1
	v_permlane16_swap_b32_e32 v151, v153
	v_add_f32_e32 v151, v151, v153
	v_mov_b32_e32 v153, v151
	s_nop 1
	v_permlane32_swap_b32_e32 v151, v153
	v_add_f32_e32 v151, v151, v153
	v_fmamk_f32 v151, v151, 0x3a800000, v198
	v_rsq_f32_e32 v151, v151
	s_and_saveexec_b64 s[58:59], s[4:5]
	s_cbranch_execz .LBB0_43
	s_lshl_b64 s[62:63], s[56:57], 2
	s_add_u32 s62, s66, s62
	s_addc_u32 s63, s67, s63
	global_store_dword v133, v151, s[62:63]

; #define LAS __attribute__((address_space(3)))
; __device__ __forceinline__ unsigned pk2(float lo, float hi) { const f32x2_pk v = {lo, hi}; return __builtin_bit_cast(unsigned, __builtin_convertvector(v, bf16x2_pk)); }
; __device__ __forceinline__ float bf1(bf16 v) { return __uint_as_float((unsigned)v << 16); }
; __device__ __forceinline__ float sigm(float x) { return __builtin_amdgcn_rcpf(1.0f + __expf(-x)); }
; __device__ __forceinline__ void thin_tile(LAS unsigned char* ldsb, int tile, const bf16* Z, bf16* MC, const float* wdw, const float* lng, const float* lnb, const float* wsc, int tid, int lane, int wave) {
;     ...
;         for (int i = 0; i < 8; ++i) { const int tok = wave * 8 + i; const f32x4 x = *(const LAS f32x4*)(U + tok * 256 + 4 * lane);
;             const float mean = wave_sum((x[0] + x[1]) + (x[2] + x[3])) * (1.f / 256.f); const f32x4 d = x - mean;
;             const float var = wave_sum((d[0] * d[0] + d[1] * d[1]) + (d[2] * d[2] + d[3] * d[3])) * (1.f / 256.f); const float rstd = __builtin_amdgcn_rsqf(var + EPS);
;             f32x4 y = d * rstd * g4 + b4; y[0] *= sigm(y[0]); y[1] *= sigm(y[1]); y[2] *= sigm(y[2]); y[3] *= sigm(y[3]);
;             v2u o; o.x = pk2(y[0], y[1]); o.y = pk2(y[2], y[3]); *(v2u*)(MC + (rowbase + t0 + tok) * DM + 4 * lane) = o; }
;     }
;     __syncthreads();
;     const int ts = t0 + half * 32;
;     {
;         const float w0 = wsc[c], w1 = wsc[256 + c], w2 = wsc[512 + c];
;         float gm2 = 0.f, gm1 = 0.f;
;         if (ts >= 2) { const bf16* zp = Z + (rowbase + ts - 2) * ZP; gm2 = bf1(zp[1792 + c]) * bf1(zp[1280 + c]); zp += ZP; gm1 = bf1(zp[1792 + c]) * bf1(zp[1280 + c]); }
.LBB0_301:
	ds_read_b128 v[34:37], v32
	s_waitcnt lgkmcnt(0)
	v_mov_b32_e32 v26, v35
	v_mov_b32_e32 v27, v36
	v_mov_b32_e32 v38, v34
	v_mov_b32_e32 v39, v37
	v_pk_add_f32 v[26:27], v[26:27], v[38:39]
	s_nop 0
	v_add_f32_e32 v26, v26, v27
	ds_bpermute_b32 v27, v0, v26
	s_waitcnt lgkmcnt(0)
	v_add_f32_e32 v26, v26, v27
	ds_bpermute_b32 v27, v23, v26
	s_waitcnt lgkmcnt(0)
	v_add_f32_e32 v26, v26, v27
	ds_bpermute_b32 v27, v28, v26
	s_waitcnt lgkmcnt(0)
	v_add_f32_e32 v26, v26, v27
	ds_bpermute_b32 v27, v29, v26
	s_waitcnt lgkmcnt(0)
	v_add_f32_e32 v26, v26, v27
	ds_bpermute_b32 v27, v30, v26
	s_waitcnt lgkmcnt(0)
	v_add_f32_e32 v26, v26, v27
	ds_bpermute_b32 v27, v31, v26
	s_waitcnt lgkmcnt(0)
	v_add_f32_e32 v33, v26, v27
	v_fmamk_f32 v27, v33, 0xbb800000, v35
	v_fmamk_f32 v26, v33, 0xbb800000, v34
	v_fmamk_f32 v37, v33, 0xbb800000, v37
	v_fmac_f32_e32 v36, 0xbb800000, v33
	v_pk_mul_f32 v[34:35], v[36:37], v[36:37]
	v_pk_mul_f32 v[38:39], v[26:27], v[26:27]
	s_nop 0
	v_pk_mov_b32 v[40:41], v[38:39], v[34:35] op_sel:[1,0]
	v_mov_b32_e32 v39, v35
	v_pk_add_f32 v[34:35], v[40:41], v[38:39]
	s_nop 0
	v_add_f32_e32 v33, v34, v35
	s_waitcnt lgkmcnt(0)
	s_nop 1
	v_add_f32_dpp v33, v33, v33 quad_perm:[1,0,3,2] row_mask:0xf bank_mask:0xf
	s_nop 1
	v_add_f32_dpp v33, v33, v33 quad_perm:[2,3,0,1] row_mask:0xf bank_mask:0xf
	s_nop 1
	v_add_f32_dpp v33, v33, v33 row_half_mirror row_mask:0xf bank_mask:0xf
	s_nop 1
	v_add_f32_dpp v33, v33, v33 row_mirror row_mask:0xf bank_mask:0xf
	v_mov_b32_e32 v34, v33
	s_nop 1
	v_permlane16_swap_b32_e32 v33, v34
	v_add_f32_e32 v33, v33, v34
	v_mov_b32_e32 v34, v33
	s_nop 1
	v_permlane32_swap_b32_e32 v33, v34
	v_add_f32_e32 v33, v33, v34
	v_fmamk_f32 v33, v33, 0x3b800000, v214
	v_rsq_f32_e32 v34, v33
	s_nop 0
	v_pk_mul_f32 v[26:27], v[26:27], v[34:35] op_sel_hi:[1,0]
	s_nop 0
	v_pk_fma_f32 v[26:27], v[2:3], v[26:27], v[6:7]
	v_pk_mul_f32 v[34:35], v[36:37], v[34:35] op_sel_hi:[1,0]
	v_mul_f32_e32 v33, 0xbfb8aa3b, v26
	v_exp_f32_e32 v33, v33
	v_pk_fma_f32 v[34:35], v[4:5], v[34:35], v[8:9]
	v_add_f32_e32 v33, 1.0, v33
	v_rcp_f32_e32 v36, v33
	v_mul_f32_e32 v33, 0xbfb8aa3b, v27
	v_exp_f32_e32 v33, v33
	s_nop 0
	v_add_f32_e32 v33, 1.0, v33
	v_rcp_f32_e32 v37, v33
	v_mul_f32_e32 v33, 0xbfb8aa3b, v34
	v_exp_f32_e32 v33, v33
	v_pk_mul_f32 v[26:27], v[26:27], v[36:37]
	s_nop 0
	v_cvt_pk_bf16_f32 v26, v26, v27
	v_add_f32_e32 v33, 1.0, v33
	v_rcp_f32_e32 v36, v33
	v_mul_f32_e32 v33, 0xbfb8aa3b, v35
	v_exp_f32_e32 v33, v33
	s_nop 0
	v_add_f32_e32 v33, 1.0, v33
	v_rcp_f32_e32 v37, v33
	s_nop 0
	v_pk_mul_f32 v[34:35], v[34:35], v[36:37]
	s_nop 0
	v_cvt_pk_bf16_f32 v27, v34, v35
	v_lshl_add_u64 v[34:35], v[24:25], 0, s[82:83]
	v_add_co_u32_e32 v38, vcc, s94, v34
	s_add_u32 s82, s82, 0x1000
	s_nop 0
	v_addc_co_u32_e32 v39, vcc, 0, v35, vcc
	ds_read_b128 v[34:37], v32 offset:1024
	global_store_dwordx2 v[38:39], v[26:27], off
	s_addc_u32 s83, s83, 0
	v_add_u32_e32 v32, 0x800, v32
	s_cmpk_eq_i32 s82, 0x4000
	s_waitcnt lgkmcnt(0)
	v_mov_b32_e32 v26, v35
	v_mov_b32_e32 v27, v36
	v_mov_b32_e32 v40, v34
	v_mov_b32_e32 v41, v37
	v_pk_add_f32 v[26:27], v[26:27], v[40:41]
	s_nop 0
	v_add_f32_e32 v26, v26, v27
	ds_bpermute_b32 v27, v0, v26
	s_waitcnt lgkmcnt(0)
	v_add_f32_e32 v26, v26, v27
	ds_bpermute_b32 v27, v23, v26
	s_waitcnt lgkmcnt(0)
	v_add_f32_e32 v26, v26, v27
	ds_bpermute_b32 v27, v28, v26
	s_waitcnt lgkmcnt(0)
	v_add_f32_e32 v26, v26, v27
	ds_bpermute_b32 v27, v29, v26
	s_waitcnt lgkmcnt(0)
	v_add_f32_e32 v26, v26, v27
	ds_bpermute_b32 v27, v30, v26
	s_waitcnt lgkmcnt(0)
	v_add_f32_e32 v26, v26, v27
	ds_bpermute_b32 v27, v31, v26
	s_waitcnt lgkmcnt(0)
	v_add_f32_e32 v33, v26, v27
	v_fmamk_f32 v27, v33, 0xbb800000, v35
	v_fmamk_f32 v26, v33, 0xbb800000, v34
	v_fmamk_f32 v37, v33, 0xbb800000, v37
	v_fmac_f32_e32 v36, 0xbb800000, v33
	v_pk_mul_f32 v[34:35], v[36:37], v[36:37]
	v_pk_mul_f32 v[40:41], v[26:27], v[26:27]
	s_nop 0
	v_pk_mov_b32 v[42:43], v[40:41], v[34:35] op_sel:[1,0]
	v_mov_b32_e32 v41, v35
	v_pk_add_f32 v[34:35], v[42:43], v[40:41]
	s_nop 0
	v_add_f32_e32 v33, v34, v35
	s_waitcnt lgkmcnt(0)
	s_nop 1
	v_add_f32_dpp v33, v33, v33 quad_perm:[1,0,3,2] row_mask:0xf bank_mask:0xf
	s_nop 1
	v_add_f32_dpp v33, v33, v33 quad_perm:[2,3,0,1] row_mask:0xf bank_mask:0xf
	s_nop 1
	v_add_f32_dpp v33, v33, v33 row_half_mirror row_mask:0xf bank_mask:0xf
	s_nop 1
	v_add_f32_dpp v33, v33, v33 row_mirror row_mask:0xf bank_mask:0xf
	v_mov_b32_e32 v34, v33
	s_nop 1
	v_permlane16_swap_b32_e32 v33, v34
	v_add_f32_e32 v33, v33, v34
	v_mov_b32_e32 v34, v33
	s_nop 1
	v_permlane32_swap_b32_e32 v33, v34
	v_add_f32_e32 v33, v33, v34
	v_fmamk_f32 v33, v33, 0x3b800000, v214
	v_rsq_f32_e32 v34, v33
	s_nop 0
	v_pk_mul_f32 v[26:27], v[26:27], v[34:35] op_sel_hi:[1,0]
	s_nop 0
	v_pk_fma_f32 v[26:27], v[2:3], v[26:27], v[6:7]
	v_pk_mul_f32 v[34:35], v[36:37], v[34:35] op_sel_hi:[1,0]
	v_mul_f32_e32 v33, 0xbfb8aa3b, v26
	v_exp_f32_e32 v33, v33
	v_pk_fma_f32 v[34:35], v[4:5], v[34:35], v[8:9]
	v_add_f32_e32 v33, 1.0, v33
	v_rcp_f32_e32 v36, v33
	v_mul_f32_e32 v33, 0xbfb8aa3b, v27
	v_exp_f32_e32 v33, v33
	s_nop 0
	v_add_f32_e32 v33, 1.0, v33
	v_rcp_f32_e32 v37, v33
	v_mul_f32_e32 v33, 0xbfb8aa3b, v34
	v_exp_f32_e32 v33, v33
	v_pk_mul_f32 v[26:27], v[26:27], v[36:37]
	s_nop 0
	v_cvt_pk_bf16_f32 v26, v26, v27
	v_add_f32_e32 v33, 1.0, v33
	v_rcp_f32_e32 v36, v33
	v_mul_f32_e32 v33, 0xbfb8aa3b, v35
	v_exp_f32_e32 v33, v33
	s_nop 0
	v_add_f32_e32 v33, 1.0, v33
	v_rcp_f32_e32 v37, v33
	s_nop 0
	v_pk_mul_f32 v[34:35], v[34:35], v[36:37]
	s_nop 0
	v_cvt_pk_bf16_f32 v27, v34, v35
	global_store_dwordx2 v[38:39], v[26:27], off offset:2048
	s_cbranch_scc0 .LBB0_301
	s_add_u32 s62, s80, s72
	s_addc_u32 s63, s81, s73
	s_barrier
	global_load_dword v23, v22, s[62:63]
	global_load_dword v28, v22, s[62:63] offset:1024
	global_load_dword v29, v22, s[62:63] offset:2048
	v_add_u32_e32 v4, s46, v152
	v_cmp_lt_i32_e32 vcc, 1, v4
	v_mov_b32_e32 v24, v1
	v_mov_b32_e32 v25, v1
	v_lshlrev_b32_e32 v0, 1, v12
	s_and_saveexec_b64 s[80:81], vcc
	s_cbranch_execz .LBB0_304
	v_mov_b32_e32 v5, v1
	v_lshl_add_u64 v[2:3], s[76:77], 0, v[4:5]
	v_mov_b64_e32 v[6:7], s[74:75]
	v_mad_u64_u32 v[6:7], s[62:63], v2, s97, v[6:7]
	s_movk_i32 s62, 0xdc00
	v_mad_i32_i24 v7, v3, s97, v7
	s_mov_b32 s63, -1
	v_lshl_add_u64 v[2:3], v[6:7], 0, s[62:63]
	v_lshlrev_b32_e32 v8, 1, v16
	v_mov_b32_e32 v9, v1
	v_lshl_add_u64 v[8:9], v[2:3], 0, v[8:9]
	v_lshlrev_b32_e32 v24, 1, v14
	v_mov_b32_e32 v25, v1
	v_lshl_add_u64 v[6:7], v[6:7], 0, v[0:1]
	v_lshl_add_u64 v[2:3], v[2:3], 0, v[24:25]
	global_load_ushort v5, v[6:7], off offset:-1024
	s_nop 0
	global_load_ushort v6, v[6:7], off offset:-2048
	s_nop 0
	global_load_ushort v8, v[8:9], off
	s_nop 0
	global_load_ushort v9, v[2:3], off
	s_waitcnt vmcnt(3)
	v_lshlrev_b32_e32 v3, 16, v5
	s_waitcnt vmcnt(2)
	v_lshlrev_b32_e32 v7, 16, v6
	s_waitcnt vmcnt(1)
	v_lshlrev_b32_e32 v2, 16, v8
	s_waitcnt vmcnt(0)
	v_lshlrev_b32_e32 v6, 16, v9
	v_pk_mul_f32 v[24:25], v[2:3], v[6:7]
